# placement: GUP body shifted +4 bytes (one s_nop at a once-per-phase spot), everything else as previous version
# baseline (speedup 1.0000x reference)
.LBB0_228:
	s_nop 0
	s_mov_b64 s[26:27], 0

.LBB0_280:
	s_nop 0
	s_nop 0
	s_nop 0
	s_nop 0
	s_nop 0
	s_nop 0
	s_nop 0
	s_nop 0
	s_nop 0
	s_nop 0
	s_nop 0
	s_nop 0
	s_nop 0
	s_nop 0
	s_mov_b64 s[26:27], 0
